# slc: fused dual-set tile (K/V fragments read from LDS once for both query sets of a wave when both selected the block)
# speedup vs baseline: 1.0273x; 1.0083x over previous
.Lpoll_done_fast:
	v_add3_u32 v233, s55, v142, v172
	v_add3_u32 v234, s55, v175, v173
	s_cmp_eq_u64 s[68:69], 0
	s_cbranch_scc1 .Lft_onlyB
	s_cmp_eq_u64 s[70:71], 0
	s_cbranch_scc1 .Lft_onlyA
	ds_read_b128 v[118:121], v233 offset:0
	ds_read_b128 v[122:125], v233 offset:4608
	ds_read_b128 v[126:129], v233 offset:9216
	ds_read_b128 v[130:133], v233 offset:13824
	v_cndmask_b32_e64 v228, v144, v64, s[8:9]
	v_cndmask_b32_e64 v229, v145, v65, s[8:9]
	v_and_b32_e32 v228, s56, v228
	v_and_b32_e32 v229, s57, v229
	v_cmp_ne_u64_e32 vcc, 0, v[228:229]
	s_nop 1
	v_cndmask_b32_e32 v220, v165, v184, vcc
	v_xor_b32_e32 v220, 0x80000000, v220
	v_mov_b32_e32 v221, v220
	v_mov_b32_e32 v222, v220
	v_mov_b32_e32 v223, v220
	v_cndmask_b32_e64 v228, v66, v146, s[8:9]
	v_cndmask_b32_e64 v229, v67, v147, s[8:9]
	v_and_b32_e32 v228, s56, v228
	v_and_b32_e32 v229, s57, v229
	v_cmp_ne_u64_e32 vcc, 0, v[228:229]
	s_nop 1
	v_cndmask_b32_e32 v224, v165, v185, vcc
	v_xor_b32_e32 v224, 0x80000000, v224
	v_mov_b32_e32 v225, v224
	v_mov_b32_e32 v226, v224
	v_mov_b32_e32 v227, v224
	s_waitcnt lgkmcnt(0)
	s_nop 0
	v_mfma_f32_16x16x32_bf16 v[188:191], v[118:121], v[70:73], v[220:223]
	v_mfma_f32_16x16x32_bf16 v[192:195], v[122:125], v[70:73], v[220:223]
	v_mfma_f32_16x16x32_bf16 v[196:199], v[126:129], v[70:73], v[220:223]
	v_mfma_f32_16x16x32_bf16 v[200:203], v[130:133], v[70:73], v[220:223]
	v_mfma_f32_16x16x32_bf16 v[204:207], v[118:121], v[86:89], v[224:227]
	v_mfma_f32_16x16x32_bf16 v[208:211], v[122:125], v[86:89], v[224:227]
	v_mfma_f32_16x16x32_bf16 v[212:215], v[126:129], v[86:89], v[224:227]
	v_mfma_f32_16x16x32_bf16 v[216:219], v[130:133], v[86:89], v[224:227]
	ds_read_b128 v[118:121], v233 offset:64
	ds_read_b128 v[122:125], v233 offset:4672
	ds_read_b128 v[126:129], v233 offset:9280
	ds_read_b128 v[130:133], v233 offset:13888
	s_waitcnt lgkmcnt(0)
	v_mfma_f32_16x16x32_bf16 v[188:191], v[118:121], v[74:77], v[188:191]
	v_mfma_f32_16x16x32_bf16 v[192:195], v[122:125], v[74:77], v[192:195]
	v_mfma_f32_16x16x32_bf16 v[196:199], v[126:129], v[74:77], v[196:199]
	v_mfma_f32_16x16x32_bf16 v[200:203], v[130:133], v[74:77], v[200:203]
	v_mfma_f32_16x16x32_bf16 v[204:207], v[118:121], v[90:93], v[204:207]
	v_mfma_f32_16x16x32_bf16 v[208:211], v[122:125], v[90:93], v[208:211]
	v_mfma_f32_16x16x32_bf16 v[212:215], v[126:129], v[90:93], v[212:215]
	v_mfma_f32_16x16x32_bf16 v[216:219], v[130:133], v[90:93], v[216:219]
	ds_read_b128 v[118:121], v233 offset:128
	ds_read_b128 v[122:125], v233 offset:4736
	ds_read_b128 v[126:129], v233 offset:9344
	ds_read_b128 v[130:133], v233 offset:13952
	s_waitcnt lgkmcnt(0)
	v_mfma_f32_16x16x32_bf16 v[188:191], v[118:121], v[78:81], v[188:191]
	v_mfma_f32_16x16x32_bf16 v[192:195], v[122:125], v[78:81], v[192:195]
	v_mfma_f32_16x16x32_bf16 v[196:199], v[126:129], v[78:81], v[196:199]
	v_mfma_f32_16x16x32_bf16 v[200:203], v[130:133], v[78:81], v[200:203]
	v_mfma_f32_16x16x32_bf16 v[204:207], v[118:121], v[94:97], v[204:207]
	v_mfma_f32_16x16x32_bf16 v[208:211], v[122:125], v[94:97], v[208:211]
	v_mfma_f32_16x16x32_bf16 v[212:215], v[126:129], v[94:97], v[212:215]
	v_mfma_f32_16x16x32_bf16 v[216:219], v[130:133], v[94:97], v[216:219]
	ds_read_b128 v[118:121], v233 offset:192
	ds_read_b128 v[122:125], v233 offset:4800
	ds_read_b128 v[126:129], v233 offset:9408
	ds_read_b128 v[130:133], v233 offset:14016
	s_waitcnt lgkmcnt(0)
	v_mfma_f32_16x16x32_bf16 v[188:191], v[118:121], v[82:85], v[188:191]
	v_mfma_f32_16x16x32_bf16 v[192:195], v[122:125], v[82:85], v[192:195]
	v_mfma_f32_16x16x32_bf16 v[196:199], v[126:129], v[82:85], v[196:199]
	v_mfma_f32_16x16x32_bf16 v[200:203], v[130:133], v[82:85], v[200:203]
	v_mfma_f32_16x16x32_bf16 v[204:207], v[118:121], v[98:101], v[204:207]
	v_mfma_f32_16x16x32_bf16 v[208:211], v[122:125], v[98:101], v[208:211]
	v_mfma_f32_16x16x32_bf16 v[212:215], v[126:129], v[98:101], v[212:215]
	v_mfma_f32_16x16x32_bf16 v[216:219], v[130:133], v[98:101], v[216:219]
	ds_read_b64_tr_b16 v[118:119], v234 offset:18432
	ds_read_b64_tr_b16 v[120:121], v234 offset:23040
	ds_read_b64_tr_b16 v[122:123], v234 offset:18464
	ds_read_b64_tr_b16 v[124:125], v234 offset:23072
	ds_read_b64_tr_b16 v[126:127], v234 offset:18496
	ds_read_b64_tr_b16 v[128:129], v234 offset:23104
	ds_read_b64_tr_b16 v[130:131], v234 offset:18528
	ds_read_b64_tr_b16 v[132:133], v234 offset:23136
	v_max3_f32 v235, v188, v189, v190
	v_max3_f32 v236, v191, v192, v193
	v_max3_f32 v235, v235, v194, v195
	v_max3_f32 v236, v236, v196, v197
	v_max3_f32 v235, v235, v198, v199
	v_max3_f32 v236, v236, v200, v201
	v_max3_f32 v235, v235, v202, v203
	v_max_f32_e32 v235, v235, v236
	v_cmp_lt_f32_e32 vcc, 0x41000000, v235
	s_cbranch_vccnz .Lft_rescale_slcDA
.Lft_resume_slcDA:
	v_exp_f32_e32 v188, v188
	v_exp_f32_e32 v189, v189
	v_add_f32_e32 v169, v169, v188
	v_exp_f32_e32 v190, v190
	v_add_f32_e32 v169, v169, v189
	v_exp_f32_e32 v191, v191
	v_add_f32_e32 v169, v169, v190
	v_exp_f32_e32 v192, v192
	v_add_f32_e32 v169, v169, v191
	v_exp_f32_e32 v193, v193
	v_add_f32_e32 v169, v169, v192
	v_exp_f32_e32 v194, v194
	v_add_f32_e32 v169, v169, v193
	v_exp_f32_e32 v195, v195
	v_add_f32_e32 v169, v169, v194
	s_nop 0
	v_add_f32_e32 v169, v169, v195
	v_cvt_pk_bf16_f32 v188, v188, v189
	v_cvt_pk_bf16_f32 v189, v190, v191
	v_cvt_pk_bf16_f32 v190, v192, v193
	v_cvt_pk_bf16_f32 v191, v194, v195
	v_exp_f32_e32 v196, v196
	v_exp_f32_e32 v197, v197
	v_add_f32_e32 v169, v169, v196
	v_exp_f32_e32 v198, v198
	v_add_f32_e32 v169, v169, v197
	v_exp_f32_e32 v199, v199
	v_add_f32_e32 v169, v169, v198
	v_exp_f32_e32 v200, v200
	v_add_f32_e32 v169, v169, v199
	v_exp_f32_e32 v201, v201
	v_add_f32_e32 v169, v169, v200
	v_exp_f32_e32 v202, v202
	v_add_f32_e32 v169, v169, v201
	v_exp_f32_e32 v203, v203
	v_add_f32_e32 v169, v169, v202
	s_nop 0
	v_add_f32_e32 v169, v169, v203
	v_cvt_pk_bf16_f32 v192, v196, v197
	v_cvt_pk_bf16_f32 v193, v198, v199
	v_cvt_pk_bf16_f32 v194, v200, v201
	v_cvt_pk_bf16_f32 v195, v202, v203
	v_max3_f32 v235, v204, v205, v206
	v_max3_f32 v236, v207, v208, v209
	v_max3_f32 v235, v235, v210, v211
	v_max3_f32 v236, v236, v212, v213
	v_max3_f32 v235, v235, v214, v215
	v_max3_f32 v236, v236, v216, v217
	v_max3_f32 v235, v235, v218, v219
	v_max_f32_e32 v235, v235, v236
	v_cmp_lt_f32_e32 vcc, 0x41000000, v235
	s_cbranch_vccnz .Lft_rescale_slcDB
.Lft_resume_slcDB:
	v_exp_f32_e32 v204, v204
	v_exp_f32_e32 v205, v205
	v_add_f32_e32 v168, v168, v204
	v_exp_f32_e32 v206, v206
	v_add_f32_e32 v168, v168, v205
	v_exp_f32_e32 v207, v207
	v_add_f32_e32 v168, v168, v206
	v_exp_f32_e32 v208, v208
	v_add_f32_e32 v168, v168, v207
	v_exp_f32_e32 v209, v209
	v_add_f32_e32 v168, v168, v208
	v_exp_f32_e32 v210, v210
	v_add_f32_e32 v168, v168, v209
	v_exp_f32_e32 v211, v211
	v_add_f32_e32 v168, v168, v210
	s_nop 0
	v_add_f32_e32 v168, v168, v211
	v_cvt_pk_bf16_f32 v204, v204, v205
	v_cvt_pk_bf16_f32 v205, v206, v207
	v_cvt_pk_bf16_f32 v206, v208, v209
	v_cvt_pk_bf16_f32 v207, v210, v211
	v_exp_f32_e32 v212, v212
	v_exp_f32_e32 v213, v213
	v_add_f32_e32 v168, v168, v212
	v_exp_f32_e32 v214, v214
	v_add_f32_e32 v168, v168, v213
	v_exp_f32_e32 v215, v215
	v_add_f32_e32 v168, v168, v214
	v_exp_f32_e32 v216, v216
	v_add_f32_e32 v168, v168, v215
	v_exp_f32_e32 v217, v217
	v_add_f32_e32 v168, v168, v216
	v_exp_f32_e32 v218, v218
	v_add_f32_e32 v168, v168, v217
	v_exp_f32_e32 v219, v219
	v_add_f32_e32 v168, v168, v218
	s_nop 0
	v_add_f32_e32 v168, v168, v219
	v_cvt_pk_bf16_f32 v208, v212, v213
	v_cvt_pk_bf16_f32 v209, v214, v215
	v_cvt_pk_bf16_f32 v210, v216, v217
	v_cvt_pk_bf16_f32 v211, v218, v219
	s_waitcnt lgkmcnt(7)
	ds_read_b64_tr_b16 v[196:197], v234 offset:18560
	ds_read_b64_tr_b16 v[198:199], v234 offset:23168
	ds_read_b64_tr_b16 v[200:201], v234 offset:18592
	ds_read_b64_tr_b16 v[202:203], v234 offset:23200
	ds_read_b64_tr_b16 v[212:213], v234 offset:18624
	ds_read_b64_tr_b16 v[214:215], v234 offset:23232
	ds_read_b64_tr_b16 v[216:217], v234 offset:18656
	ds_read_b64_tr_b16 v[218:219], v234 offset:23264
	s_waitcnt lgkmcnt(8)
	v_mfma_f32_16x16x32_bf16 v[60:63], v[118:121], v[188:191], v[60:63]
	v_mfma_f32_16x16x32_bf16 v[32:35], v[118:121], v[204:207], v[32:35]
	v_mfma_f32_16x16x32_bf16 v[56:59], v[122:125], v[188:191], v[56:59]
	v_mfma_f32_16x16x32_bf16 v[28:31], v[122:125], v[204:207], v[28:31]
	v_mfma_f32_16x16x32_bf16 v[52:55], v[126:129], v[188:191], v[52:55]
	v_mfma_f32_16x16x32_bf16 v[24:27], v[126:129], v[204:207], v[24:27]
	v_mfma_f32_16x16x32_bf16 v[48:51], v[130:133], v[188:191], v[48:51]
	v_mfma_f32_16x16x32_bf16 v[20:23], v[130:133], v[204:207], v[20:23]
	s_waitcnt lgkmcnt(7)
	ds_read_b64_tr_b16 v[118:119], v234 offset:27648
	ds_read_b64_tr_b16 v[120:121], v234 offset:32256
	ds_read_b64_tr_b16 v[122:123], v234 offset:27680
	ds_read_b64_tr_b16 v[124:125], v234 offset:32288
	ds_read_b64_tr_b16 v[126:127], v234 offset:27712
	ds_read_b64_tr_b16 v[128:129], v234 offset:32320
	ds_read_b64_tr_b16 v[130:131], v234 offset:27744
	ds_read_b64_tr_b16 v[132:133], v234 offset:32352
	s_waitcnt lgkmcnt(8)
	v_mfma_f32_16x16x32_bf16 v[44:47], v[196:199], v[188:191], v[44:47]
	v_mfma_f32_16x16x32_bf16 v[16:19], v[196:199], v[204:207], v[16:19]
	v_mfma_f32_16x16x32_bf16 v[40:43], v[200:203], v[188:191], v[40:43]
	v_mfma_f32_16x16x32_bf16 v[12:15], v[200:203], v[204:207], v[12:15]
	v_mfma_f32_16x16x32_bf16 v[36:39], v[212:215], v[188:191], v[36:39]
	v_mfma_f32_16x16x32_bf16 v[4:7], v[212:215], v[204:207], v[4:7]
	v_mfma_f32_16x16x32_bf16 v[8:11], v[216:219], v[188:191], v[8:11]
	v_mfma_f32_16x16x32_bf16 v[0:3], v[216:219], v[204:207], v[0:3]
	s_waitcnt lgkmcnt(7)
	ds_read_b64_tr_b16 v[196:197], v234 offset:27776
	ds_read_b64_tr_b16 v[198:199], v234 offset:32384
	ds_read_b64_tr_b16 v[200:201], v234 offset:27808
	ds_read_b64_tr_b16 v[202:203], v234 offset:32416
	ds_read_b64_tr_b16 v[212:213], v234 offset:27840
	ds_read_b64_tr_b16 v[214:215], v234 offset:32448
	ds_read_b64_tr_b16 v[216:217], v234 offset:27872
	ds_read_b64_tr_b16 v[218:219], v234 offset:32480
	s_waitcnt lgkmcnt(8)
	v_mfma_f32_16x16x32_bf16 v[60:63], v[118:121], v[192:195], v[60:63]
	v_mfma_f32_16x16x32_bf16 v[32:35], v[118:121], v[208:211], v[32:35]
	v_mfma_f32_16x16x32_bf16 v[56:59], v[122:125], v[192:195], v[56:59]
	v_mfma_f32_16x16x32_bf16 v[28:31], v[122:125], v[208:211], v[28:31]
	v_mfma_f32_16x16x32_bf16 v[52:55], v[126:129], v[192:195], v[52:55]
	v_mfma_f32_16x16x32_bf16 v[24:27], v[126:129], v[208:211], v[24:27]
	v_mfma_f32_16x16x32_bf16 v[48:51], v[130:133], v[192:195], v[48:51]
	v_mfma_f32_16x16x32_bf16 v[20:23], v[130:133], v[208:211], v[20:23]
	s_waitcnt lgkmcnt(0)
	v_mfma_f32_16x16x32_bf16 v[44:47], v[196:199], v[192:195], v[44:47]
	v_mfma_f32_16x16x32_bf16 v[16:19], v[196:199], v[208:211], v[16:19]
	v_mfma_f32_16x16x32_bf16 v[40:43], v[200:203], v[192:195], v[40:43]
	v_mfma_f32_16x16x32_bf16 v[12:15], v[200:203], v[208:211], v[12:15]
	v_mfma_f32_16x16x32_bf16 v[36:39], v[212:215], v[192:195], v[36:39]
	v_mfma_f32_16x16x32_bf16 v[4:7], v[212:215], v[208:211], v[4:7]
	v_mfma_f32_16x16x32_bf16 v[8:11], v[216:219], v[192:195], v[8:11]
	v_mfma_f32_16x16x32_bf16 v[0:3], v[216:219], v[208:211], v[0:3]
	s_branch .Las_s3
.Lft_onlyA:
	ds_read_b128 v[118:121], v233 offset:0
	ds_read_b128 v[122:125], v233 offset:4608
	ds_read_b128 v[126:129], v233 offset:9216
	ds_read_b128 v[130:133], v233 offset:13824
	ds_read_b128 v[204:207], v233 offset:64
	ds_read_b128 v[208:211], v233 offset:4672
	ds_read_b128 v[212:215], v233 offset:9280
	ds_read_b128 v[216:219], v233 offset:13888
	v_cndmask_b32_e64 v228, v144, v64, s[8:9]
	v_cndmask_b32_e64 v229, v145, v65, s[8:9]
	v_and_b32_e32 v228, s56, v228
	v_and_b32_e32 v229, s57, v229
	v_cmp_ne_u64_e32 vcc, 0, v[228:229]
	s_nop 1
	v_cndmask_b32_e32 v220, v165, v184, vcc
	v_xor_b32_e32 v220, 0x80000000, v220
	v_mov_b32_e32 v221, v220
	v_mov_b32_e32 v222, v220
	v_mov_b32_e32 v223, v220
	s_waitcnt lgkmcnt(4)
	s_nop 0
	v_mfma_f32_16x16x32_bf16 v[188:191], v[118:121], v[70:73], v[220:223]
	v_mfma_f32_16x16x32_bf16 v[192:195], v[122:125], v[70:73], v[220:223]
	v_mfma_f32_16x16x32_bf16 v[196:199], v[126:129], v[70:73], v[220:223]
	v_mfma_f32_16x16x32_bf16 v[200:203], v[130:133], v[70:73], v[220:223]
	ds_read_b128 v[118:121], v233 offset:128
	ds_read_b128 v[122:125], v233 offset:4736
	ds_read_b128 v[126:129], v233 offset:9344
	ds_read_b128 v[130:133], v233 offset:13952
	s_waitcnt lgkmcnt(4)
	v_mfma_f32_16x16x32_bf16 v[188:191], v[204:207], v[74:77], v[188:191]
	v_mfma_f32_16x16x32_bf16 v[192:195], v[208:211], v[74:77], v[192:195]
	v_mfma_f32_16x16x32_bf16 v[196:199], v[212:215], v[74:77], v[196:199]
	v_mfma_f32_16x16x32_bf16 v[200:203], v[216:219], v[74:77], v[200:203]
	ds_read_b128 v[204:207], v233 offset:192
	ds_read_b128 v[208:211], v233 offset:4800
	ds_read_b128 v[212:215], v233 offset:9408
	ds_read_b128 v[216:219], v233 offset:14016
	s_waitcnt lgkmcnt(4)
	v_mfma_f32_16x16x32_bf16 v[188:191], v[118:121], v[78:81], v[188:191]
	v_mfma_f32_16x16x32_bf16 v[192:195], v[122:125], v[78:81], v[192:195]
	v_mfma_f32_16x16x32_bf16 v[196:199], v[126:129], v[78:81], v[196:199]
	v_mfma_f32_16x16x32_bf16 v[200:203], v[130:133], v[78:81], v[200:203]
	s_waitcnt lgkmcnt(0)
	v_mfma_f32_16x16x32_bf16 v[188:191], v[204:207], v[82:85], v[188:191]
	v_mfma_f32_16x16x32_bf16 v[192:195], v[208:211], v[82:85], v[192:195]
	v_mfma_f32_16x16x32_bf16 v[196:199], v[212:215], v[82:85], v[196:199]
	v_mfma_f32_16x16x32_bf16 v[200:203], v[216:219], v[82:85], v[200:203]
	ds_read_b64_tr_b16 v[118:119], v234 offset:18432
	ds_read_b64_tr_b16 v[120:121], v234 offset:23040
	ds_read_b64_tr_b16 v[122:123], v234 offset:18464
	ds_read_b64_tr_b16 v[124:125], v234 offset:23072
	ds_read_b64_tr_b16 v[126:127], v234 offset:18496
	ds_read_b64_tr_b16 v[128:129], v234 offset:23104
	ds_read_b64_tr_b16 v[130:131], v234 offset:18528
	ds_read_b64_tr_b16 v[132:133], v234 offset:23136
	v_max3_f32 v235, v188, v189, v190
	v_max3_f32 v236, v191, v192, v193
	v_max3_f32 v235, v235, v194, v195
	v_max3_f32 v236, v236, v196, v197
	v_max3_f32 v235, v235, v198, v199
	v_max3_f32 v236, v236, v200, v201
	v_max3_f32 v235, v235, v202, v203
	v_max_f32_e32 v235, v235, v236
	v_cmp_lt_f32_e32 vcc, 0x41000000, v235
	s_cbranch_vccnz .Lft_rescale_slcA
.Lft_resume_slcA:
	v_exp_f32_e32 v188, v188
	v_exp_f32_e32 v189, v189
	v_add_f32_e32 v169, v169, v188
	v_exp_f32_e32 v190, v190
	v_add_f32_e32 v169, v169, v189
	v_exp_f32_e32 v191, v191
	v_add_f32_e32 v169, v169, v190
	v_exp_f32_e32 v192, v192
	v_add_f32_e32 v169, v169, v191
	v_exp_f32_e32 v193, v193
	v_add_f32_e32 v169, v169, v192
	v_exp_f32_e32 v194, v194
	v_add_f32_e32 v169, v169, v193
	v_exp_f32_e32 v195, v195
	v_add_f32_e32 v169, v169, v194
	s_nop 0
	v_add_f32_e32 v169, v169, v195
	v_cvt_pk_bf16_f32 v188, v188, v189
	v_cvt_pk_bf16_f32 v189, v190, v191
	v_cvt_pk_bf16_f32 v190, v192, v193
	v_cvt_pk_bf16_f32 v191, v194, v195
	s_waitcnt lgkmcnt(7)
	ds_read_b64_tr_b16 v[204:205], v234 offset:18560
	ds_read_b64_tr_b16 v[206:207], v234 offset:23168
	ds_read_b64_tr_b16 v[208:209], v234 offset:18592
	ds_read_b64_tr_b16 v[210:211], v234 offset:23200
	ds_read_b64_tr_b16 v[212:213], v234 offset:18624
	ds_read_b64_tr_b16 v[214:215], v234 offset:23232
	ds_read_b64_tr_b16 v[216:217], v234 offset:18656
	ds_read_b64_tr_b16 v[218:219], v234 offset:23264
	v_exp_f32_e32 v196, v196
	v_exp_f32_e32 v197, v197
	v_add_f32_e32 v169, v169, v196
	v_exp_f32_e32 v198, v198
	v_add_f32_e32 v169, v169, v197
	v_exp_f32_e32 v199, v199
	v_add_f32_e32 v169, v169, v198
	v_exp_f32_e32 v200, v200
	v_add_f32_e32 v169, v169, v199
	v_exp_f32_e32 v201, v201
	v_add_f32_e32 v169, v169, v200
	v_exp_f32_e32 v202, v202
	v_add_f32_e32 v169, v169, v201
	v_exp_f32_e32 v203, v203
	v_add_f32_e32 v169, v169, v202
	s_nop 0
	v_add_f32_e32 v169, v169, v203
	v_cvt_pk_bf16_f32 v192, v196, v197
	v_cvt_pk_bf16_f32 v193, v198, v199
	v_cvt_pk_bf16_f32 v194, v200, v201
	v_cvt_pk_bf16_f32 v195, v202, v203
	s_waitcnt lgkmcnt(8)
	v_mfma_f32_16x16x32_bf16 v[60:63], v[118:121], v[188:191], v[60:63]
	v_mfma_f32_16x16x32_bf16 v[56:59], v[122:125], v[188:191], v[56:59]
	v_mfma_f32_16x16x32_bf16 v[52:55], v[126:129], v[188:191], v[52:55]
	v_mfma_f32_16x16x32_bf16 v[48:51], v[130:133], v[188:191], v[48:51]
	ds_read_b64_tr_b16 v[118:119], v234 offset:27648
	ds_read_b64_tr_b16 v[120:121], v234 offset:32256
	ds_read_b64_tr_b16 v[122:123], v234 offset:27680
	ds_read_b64_tr_b16 v[124:125], v234 offset:32288
	ds_read_b64_tr_b16 v[126:127], v234 offset:27712
	ds_read_b64_tr_b16 v[128:129], v234 offset:32320
	ds_read_b64_tr_b16 v[130:131], v234 offset:27744
	ds_read_b64_tr_b16 v[132:133], v234 offset:32352
	s_waitcnt lgkmcnt(8)
	v_mfma_f32_16x16x32_bf16 v[44:47], v[204:207], v[188:191], v[44:47]
	v_mfma_f32_16x16x32_bf16 v[40:43], v[208:211], v[188:191], v[40:43]
	v_mfma_f32_16x16x32_bf16 v[36:39], v[212:215], v[188:191], v[36:39]
	v_mfma_f32_16x16x32_bf16 v[8:11], v[216:219], v[188:191], v[8:11]
	s_waitcnt lgkmcnt(7)
	ds_read_b64_tr_b16 v[204:205], v234 offset:27776
	ds_read_b64_tr_b16 v[206:207], v234 offset:32384
	ds_read_b64_tr_b16 v[208:209], v234 offset:27808
	ds_read_b64_tr_b16 v[210:211], v234 offset:32416
	ds_read_b64_tr_b16 v[212:213], v234 offset:27840
	ds_read_b64_tr_b16 v[214:215], v234 offset:32448
	ds_read_b64_tr_b16 v[216:217], v234 offset:27872
	ds_read_b64_tr_b16 v[218:219], v234 offset:32480
	s_waitcnt lgkmcnt(8)
	v_mfma_f32_16x16x32_bf16 v[60:63], v[118:121], v[192:195], v[60:63]
	v_mfma_f32_16x16x32_bf16 v[56:59], v[122:125], v[192:195], v[56:59]
	v_mfma_f32_16x16x32_bf16 v[52:55], v[126:129], v[192:195], v[52:55]
	v_mfma_f32_16x16x32_bf16 v[48:51], v[130:133], v[192:195], v[48:51]
	s_waitcnt lgkmcnt(0)
	v_mfma_f32_16x16x32_bf16 v[44:47], v[204:207], v[192:195], v[44:47]
	v_mfma_f32_16x16x32_bf16 v[40:43], v[208:211], v[192:195], v[40:43]
	v_mfma_f32_16x16x32_bf16 v[36:39], v[212:215], v[192:195], v[36:39]
	v_mfma_f32_16x16x32_bf16 v[8:11], v[216:219], v[192:195], v[8:11]
	s_branch .Las_s3
.Lft_onlyB:
	ds_read_b128 v[118:121], v233 offset:0
	ds_read_b128 v[122:125], v233 offset:4608
	ds_read_b128 v[126:129], v233 offset:9216
	ds_read_b128 v[130:133], v233 offset:13824
	ds_read_b128 v[204:207], v233 offset:64
	ds_read_b128 v[208:211], v233 offset:4672
	ds_read_b128 v[212:215], v233 offset:9280
	ds_read_b128 v[216:219], v233 offset:13888
	v_cndmask_b32_e64 v228, v66, v146, s[8:9]
	v_cndmask_b32_e64 v229, v67, v147, s[8:9]
	v_and_b32_e32 v228, s56, v228
	v_and_b32_e32 v229, s57, v229
	v_cmp_ne_u64_e32 vcc, 0, v[228:229]
	s_nop 1
	v_cndmask_b32_e32 v220, v165, v185, vcc
	v_xor_b32_e32 v220, 0x80000000, v220
	v_mov_b32_e32 v221, v220
	v_mov_b32_e32 v222, v220
	v_mov_b32_e32 v223, v220
	s_waitcnt lgkmcnt(4)
	s_nop 0
	v_mfma_f32_16x16x32_bf16 v[188:191], v[118:121], v[86:89], v[220:223]
	v_mfma_f32_16x16x32_bf16 v[192:195], v[122:125], v[86:89], v[220:223]
	v_mfma_f32_16x16x32_bf16 v[196:199], v[126:129], v[86:89], v[220:223]
	v_mfma_f32_16x16x32_bf16 v[200:203], v[130:133], v[86:89], v[220:223]
	ds_read_b128 v[118:121], v233 offset:128
	ds_read_b128 v[122:125], v233 offset:4736
	ds_read_b128 v[126:129], v233 offset:9344
	ds_read_b128 v[130:133], v233 offset:13952
	s_waitcnt lgkmcnt(4)
	v_mfma_f32_16x16x32_bf16 v[188:191], v[204:207], v[90:93], v[188:191]
	v_mfma_f32_16x16x32_bf16 v[192:195], v[208:211], v[90:93], v[192:195]
	v_mfma_f32_16x16x32_bf16 v[196:199], v[212:215], v[90:93], v[196:199]
	v_mfma_f32_16x16x32_bf16 v[200:203], v[216:219], v[90:93], v[200:203]
	ds_read_b128 v[204:207], v233 offset:192
	ds_read_b128 v[208:211], v233 offset:4800
	ds_read_b128 v[212:215], v233 offset:9408
	ds_read_b128 v[216:219], v233 offset:14016
	s_waitcnt lgkmcnt(4)
	v_mfma_f32_16x16x32_bf16 v[188:191], v[118:121], v[94:97], v[188:191]
	v_mfma_f32_16x16x32_bf16 v[192:195], v[122:125], v[94:97], v[192:195]
	v_mfma_f32_16x16x32_bf16 v[196:199], v[126:129], v[94:97], v[196:199]
	v_mfma_f32_16x16x32_bf16 v[200:203], v[130:133], v[94:97], v[200:203]
	s_waitcnt lgkmcnt(0)
	v_mfma_f32_16x16x32_bf16 v[188:191], v[204:207], v[98:101], v[188:191]
	v_mfma_f32_16x16x32_bf16 v[192:195], v[208:211], v[98:101], v[192:195]
	v_mfma_f32_16x16x32_bf16 v[196:199], v[212:215], v[98:101], v[196:199]
	v_mfma_f32_16x16x32_bf16 v[200:203], v[216:219], v[98:101], v[200:203]
	ds_read_b64_tr_b16 v[118:119], v234 offset:18432
	ds_read_b64_tr_b16 v[120:121], v234 offset:23040
	ds_read_b64_tr_b16 v[122:123], v234 offset:18464
	ds_read_b64_tr_b16 v[124:125], v234 offset:23072
	ds_read_b64_tr_b16 v[126:127], v234 offset:18496
	ds_read_b64_tr_b16 v[128:129], v234 offset:23104
	ds_read_b64_tr_b16 v[130:131], v234 offset:18528
	ds_read_b64_tr_b16 v[132:133], v234 offset:23136
	v_max3_f32 v235, v188, v189, v190
	v_max3_f32 v236, v191, v192, v193
	v_max3_f32 v235, v235, v194, v195
	v_max3_f32 v236, v236, v196, v197
	v_max3_f32 v235, v235, v198, v199
	v_max3_f32 v236, v236, v200, v201
	v_max3_f32 v235, v235, v202, v203
	v_max_f32_e32 v235, v235, v236
	v_cmp_lt_f32_e32 vcc, 0x41000000, v235
	s_cbranch_vccnz .Lft_rescale_slcB
.Lft_resume_slcB:
	v_exp_f32_e32 v188, v188
	v_exp_f32_e32 v189, v189
	v_add_f32_e32 v168, v168, v188
	v_exp_f32_e32 v190, v190
	v_add_f32_e32 v168, v168, v189
	v_exp_f32_e32 v191, v191
	v_add_f32_e32 v168, v168, v190
	v_exp_f32_e32 v192, v192
	v_add_f32_e32 v168, v168, v191
	v_exp_f32_e32 v193, v193
	v_add_f32_e32 v168, v168, v192
	v_exp_f32_e32 v194, v194
	v_add_f32_e32 v168, v168, v193
	v_exp_f32_e32 v195, v195
	v_add_f32_e32 v168, v168, v194
	s_nop 0
	v_add_f32_e32 v168, v168, v195
	v_cvt_pk_bf16_f32 v188, v188, v189
	v_cvt_pk_bf16_f32 v189, v190, v191
	v_cvt_pk_bf16_f32 v190, v192, v193
	v_cvt_pk_bf16_f32 v191, v194, v195
	s_waitcnt lgkmcnt(7)
	ds_read_b64_tr_b16 v[204:205], v234 offset:18560
	ds_read_b64_tr_b16 v[206:207], v234 offset:23168
	ds_read_b64_tr_b16 v[208:209], v234 offset:18592
	ds_read_b64_tr_b16 v[210:211], v234 offset:23200
	ds_read_b64_tr_b16 v[212:213], v234 offset:18624
	ds_read_b64_tr_b16 v[214:215], v234 offset:23232
	ds_read_b64_tr_b16 v[216:217], v234 offset:18656
	ds_read_b64_tr_b16 v[218:219], v234 offset:23264
	v_exp_f32_e32 v196, v196
	v_exp_f32_e32 v197, v197
	v_add_f32_e32 v168, v168, v196
	v_exp_f32_e32 v198, v198
	v_add_f32_e32 v168, v168, v197
	v_exp_f32_e32 v199, v199
	v_add_f32_e32 v168, v168, v198
	v_exp_f32_e32 v200, v200
	v_add_f32_e32 v168, v168, v199
	v_exp_f32_e32 v201, v201
	v_add_f32_e32 v168, v168, v200
	v_exp_f32_e32 v202, v202
	v_add_f32_e32 v168, v168, v201
	v_exp_f32_e32 v203, v203
	v_add_f32_e32 v168, v168, v202
	s_nop 0
	v_add_f32_e32 v168, v168, v203
	v_cvt_pk_bf16_f32 v192, v196, v197
	v_cvt_pk_bf16_f32 v193, v198, v199
	v_cvt_pk_bf16_f32 v194, v200, v201
	v_cvt_pk_bf16_f32 v195, v202, v203
	s_waitcnt lgkmcnt(8)
	v_mfma_f32_16x16x32_bf16 v[32:35], v[118:121], v[188:191], v[32:35]
	v_mfma_f32_16x16x32_bf16 v[28:31], v[122:125], v[188:191], v[28:31]
	v_mfma_f32_16x16x32_bf16 v[24:27], v[126:129], v[188:191], v[24:27]
	v_mfma_f32_16x16x32_bf16 v[20:23], v[130:133], v[188:191], v[20:23]
	ds_read_b64_tr_b16 v[118:119], v234 offset:27648
	ds_read_b64_tr_b16 v[120:121], v234 offset:32256
	ds_read_b64_tr_b16 v[122:123], v234 offset:27680
	ds_read_b64_tr_b16 v[124:125], v234 offset:32288
	ds_read_b64_tr_b16 v[126:127], v234 offset:27712
	ds_read_b64_tr_b16 v[128:129], v234 offset:32320
	ds_read_b64_tr_b16 v[130:131], v234 offset:27744
	ds_read_b64_tr_b16 v[132:133], v234 offset:32352
	s_waitcnt lgkmcnt(8)
	v_mfma_f32_16x16x32_bf16 v[16:19], v[204:207], v[188:191], v[16:19]
	v_mfma_f32_16x16x32_bf16 v[12:15], v[208:211], v[188:191], v[12:15]
	v_mfma_f32_16x16x32_bf16 v[4:7], v[212:215], v[188:191], v[4:7]
	v_mfma_f32_16x16x32_bf16 v[0:3], v[216:219], v[188:191], v[0:3]
	s_waitcnt lgkmcnt(7)
	ds_read_b64_tr_b16 v[204:205], v234 offset:27776
	ds_read_b64_tr_b16 v[206:207], v234 offset:32384
	ds_read_b64_tr_b16 v[208:209], v234 offset:27808
	ds_read_b64_tr_b16 v[210:211], v234 offset:32416
	ds_read_b64_tr_b16 v[212:213], v234 offset:27840
	ds_read_b64_tr_b16 v[214:215], v234 offset:32448
	ds_read_b64_tr_b16 v[216:217], v234 offset:27872
	ds_read_b64_tr_b16 v[218:219], v234 offset:32480
	s_waitcnt lgkmcnt(8)
	v_mfma_f32_16x16x32_bf16 v[32:35], v[118:121], v[192:195], v[32:35]
	v_mfma_f32_16x16x32_bf16 v[28:31], v[122:125], v[192:195], v[28:31]
	v_mfma_f32_16x16x32_bf16 v[24:27], v[126:129], v[192:195], v[24:27]
	v_mfma_f32_16x16x32_bf16 v[20:23], v[130:133], v[192:195], v[20:23]
	s_waitcnt lgkmcnt(0)
	v_mfma_f32_16x16x32_bf16 v[16:19], v[204:207], v[192:195], v[16:19]
	v_mfma_f32_16x16x32_bf16 v[12:15], v[208:211], v[192:195], v[12:15]
	v_mfma_f32_16x16x32_bf16 v[4:7], v[212:215], v[192:195], v[4:7]
	v_mfma_f32_16x16x32_bf16 v[0:3], v[216:219], v[192:195], v[0:3]

.Lft_rescale_slcA:
	v_mov_b32_e32 v236, v235
	s_nop 1
	v_permlane16_swap_b32_e32 v235, v236
	v_max_f32_e32 v236, v236, v235
	v_mov_b32_e32 v235, v236
	s_nop 1
	v_permlane32_swap_b32_e32 v236, v235
	v_max_f32_e32 v235, v236, v235
	v_max_f32_e32 v235, 0, v235
	v_add_f32_e32 v184, v184, v235
	v_sub_f32_e32 v228, 0, v235
	v_exp_f32_e32 v228, v228
	v_sub_f32_e32 v188, v188, v235
	v_sub_f32_e32 v189, v189, v235
	v_sub_f32_e32 v190, v190, v235
	v_sub_f32_e32 v191, v191, v235
	v_sub_f32_e32 v192, v192, v235
	v_sub_f32_e32 v193, v193, v235
	v_sub_f32_e32 v194, v194, v235
	v_sub_f32_e32 v195, v195, v235
	v_sub_f32_e32 v196, v196, v235
	v_sub_f32_e32 v197, v197, v235
	v_sub_f32_e32 v198, v198, v235
	v_sub_f32_e32 v199, v199, v235
	v_sub_f32_e32 v200, v200, v235
	v_sub_f32_e32 v201, v201, v235
	v_sub_f32_e32 v202, v202, v235
	v_sub_f32_e32 v203, v203, v235
	v_mul_f32_e32 v169, v169, v228
	v_pk_mul_f32 v[60:61], v[60:61], v[228:229] op_sel_hi:[1,0]
	v_pk_mul_f32 v[62:63], v[62:63], v[228:229] op_sel_hi:[1,0]
	v_pk_mul_f32 v[56:57], v[56:57], v[228:229] op_sel_hi:[1,0]
	v_pk_mul_f32 v[58:59], v[58:59], v[228:229] op_sel_hi:[1,0]
	v_pk_mul_f32 v[52:53], v[52:53], v[228:229] op_sel_hi:[1,0]
	v_pk_mul_f32 v[54:55], v[54:55], v[228:229] op_sel_hi:[1,0]
	v_pk_mul_f32 v[48:49], v[48:49], v[228:229] op_sel_hi:[1,0]
	v_pk_mul_f32 v[50:51], v[50:51], v[228:229] op_sel_hi:[1,0]
	v_pk_mul_f32 v[44:45], v[44:45], v[228:229] op_sel_hi:[1,0]
	v_pk_mul_f32 v[46:47], v[46:47], v[228:229] op_sel_hi:[1,0]
	v_pk_mul_f32 v[40:41], v[40:41], v[228:229] op_sel_hi:[1,0]
	v_pk_mul_f32 v[42:43], v[42:43], v[228:229] op_sel_hi:[1,0]
	v_pk_mul_f32 v[36:37], v[36:37], v[228:229] op_sel_hi:[1,0]
	v_pk_mul_f32 v[38:39], v[38:39], v[228:229] op_sel_hi:[1,0]
	v_pk_mul_f32 v[8:9], v[8:9], v[228:229] op_sel_hi:[1,0]
	v_pk_mul_f32 v[10:11], v[10:11], v[228:229] op_sel_hi:[1,0]
	s_branch .Lft_resume_slcA
.Lft_rescale_slcB:
	v_mov_b32_e32 v236, v235
	s_nop 1
	v_permlane16_swap_b32_e32 v235, v236
	v_max_f32_e32 v236, v236, v235
	v_mov_b32_e32 v235, v236
	s_nop 1
	v_permlane32_swap_b32_e32 v236, v235
	v_max_f32_e32 v235, v236, v235
	v_max_f32_e32 v235, 0, v235
	v_add_f32_e32 v185, v185, v235
	v_sub_f32_e32 v228, 0, v235
	v_exp_f32_e32 v228, v228
	v_sub_f32_e32 v188, v188, v235
	v_sub_f32_e32 v189, v189, v235
	v_sub_f32_e32 v190, v190, v235
	v_sub_f32_e32 v191, v191, v235
	v_sub_f32_e32 v192, v192, v235
	v_sub_f32_e32 v193, v193, v235
	v_sub_f32_e32 v194, v194, v235
	v_sub_f32_e32 v195, v195, v235
	v_sub_f32_e32 v196, v196, v235
	v_sub_f32_e32 v197, v197, v235
	v_sub_f32_e32 v198, v198, v235
	v_sub_f32_e32 v199, v199, v235
	v_sub_f32_e32 v200, v200, v235
	v_sub_f32_e32 v201, v201, v235
	v_sub_f32_e32 v202, v202, v235
	v_sub_f32_e32 v203, v203, v235
	v_mul_f32_e32 v168, v168, v228
	v_pk_mul_f32 v[32:33], v[32:33], v[228:229] op_sel_hi:[1,0]
	v_pk_mul_f32 v[34:35], v[34:35], v[228:229] op_sel_hi:[1,0]
	v_pk_mul_f32 v[28:29], v[28:29], v[228:229] op_sel_hi:[1,0]
	v_pk_mul_f32 v[30:31], v[30:31], v[228:229] op_sel_hi:[1,0]
	v_pk_mul_f32 v[24:25], v[24:25], v[228:229] op_sel_hi:[1,0]
	v_pk_mul_f32 v[26:27], v[26:27], v[228:229] op_sel_hi:[1,0]
	v_pk_mul_f32 v[20:21], v[20:21], v[228:229] op_sel_hi:[1,0]
	v_pk_mul_f32 v[22:23], v[22:23], v[228:229] op_sel_hi:[1,0]
	v_pk_mul_f32 v[16:17], v[16:17], v[228:229] op_sel_hi:[1,0]
	v_pk_mul_f32 v[18:19], v[18:19], v[228:229] op_sel_hi:[1,0]
	v_pk_mul_f32 v[12:13], v[12:13], v[228:229] op_sel_hi:[1,0]
	v_pk_mul_f32 v[14:15], v[14:15], v[228:229] op_sel_hi:[1,0]
	v_pk_mul_f32 v[4:5], v[4:5], v[228:229] op_sel_hi:[1,0]
	v_pk_mul_f32 v[6:7], v[6:7], v[228:229] op_sel_hi:[1,0]
	v_pk_mul_f32 v[0:1], v[0:1], v[228:229] op_sel_hi:[1,0]
	v_pk_mul_f32 v[2:3], v[2:3], v[228:229] op_sel_hi:[1,0]
	s_branch .Lft_resume_slcB

.Lft_rescale_slcDB:
	v_mov_b32_e32 v236, v235
	s_nop 1
	v_permlane16_swap_b32_e32 v235, v236
	v_max_f32_e32 v236, v236, v235
	v_mov_b32_e32 v235, v236
	s_nop 1
	v_permlane32_swap_b32_e32 v236, v235
	v_max_f32_e32 v235, v236, v235
	v_max_f32_e32 v235, 0, v235
	v_add_f32_e32 v185, v185, v235
	v_sub_f32_e32 v228, 0, v235
	v_exp_f32_e32 v228, v228
	v_sub_f32_e32 v204, v204, v235
	v_sub_f32_e32 v205, v205, v235
	v_sub_f32_e32 v206, v206, v235
	v_sub_f32_e32 v207, v207, v235
	v_sub_f32_e32 v208, v208, v235
	v_sub_f32_e32 v209, v209, v235
	v_sub_f32_e32 v210, v210, v235
	v_sub_f32_e32 v211, v211, v235
	v_sub_f32_e32 v212, v212, v235
	v_sub_f32_e32 v213, v213, v235
	v_sub_f32_e32 v214, v214, v235
	v_sub_f32_e32 v215, v215, v235
	v_sub_f32_e32 v216, v216, v235
	v_sub_f32_e32 v217, v217, v235
	v_sub_f32_e32 v218, v218, v235
	v_sub_f32_e32 v219, v219, v235
	v_mul_f32_e32 v168, v168, v228
	v_pk_mul_f32 v[32:33], v[32:33], v[228:229] op_sel_hi:[1,0]
	v_pk_mul_f32 v[34:35], v[34:35], v[228:229] op_sel_hi:[1,0]
	v_pk_mul_f32 v[28:29], v[28:29], v[228:229] op_sel_hi:[1,0]
	v_pk_mul_f32 v[30:31], v[30:31], v[228:229] op_sel_hi:[1,0]
	v_pk_mul_f32 v[24:25], v[24:25], v[228:229] op_sel_hi:[1,0]
	v_pk_mul_f32 v[26:27], v[26:27], v[228:229] op_sel_hi:[1,0]
	v_pk_mul_f32 v[20:21], v[20:21], v[228:229] op_sel_hi:[1,0]
	v_pk_mul_f32 v[22:23], v[22:23], v[228:229] op_sel_hi:[1,0]
	v_pk_mul_f32 v[16:17], v[16:17], v[228:229] op_sel_hi:[1,0]
	v_pk_mul_f32 v[18:19], v[18:19], v[228:229] op_sel_hi:[1,0]
	v_pk_mul_f32 v[12:13], v[12:13], v[228:229] op_sel_hi:[1,0]
	v_pk_mul_f32 v[14:15], v[14:15], v[228:229] op_sel_hi:[1,0]
	v_pk_mul_f32 v[4:5], v[4:5], v[228:229] op_sel_hi:[1,0]
	v_pk_mul_f32 v[6:7], v[6:7], v[228:229] op_sel_hi:[1,0]
	v_pk_mul_f32 v[0:1], v[0:1], v[228:229] op_sel_hi:[1,0]
	v_pk_mul_f32 v[2:3], v[2:3], v[228:229] op_sel_hi:[1,0]
	s_branch .Lft_resume_slcDB
